# filter producer moved from phase 2 into phase 1 (before / after the modulate chunk by workgroup group)
# baseline (speedup 1.0000x reference)
.LBB0_135:
.LBB0_136:
	s_cmp_lt_i32 s68, 2
	s_cselect_b64 s[8:9], -1, 0
	s_and_b64 s[36:37], s[8:9], s[6:7]
	s_andn2_b64 vcc, exec, s[36:37]
	s_cbranch_vccnz .LBB0_140
	s_cmpk_lg_u32 s70, 0x100
	s_cbranch_scc1 .Lp1_body
	s_bitcmp1_b32 s2, 3
	s_cbranch_scc1 .Lpf_begin
.Lp1_body:
	s_cmpk_gt_i32 s2, 0xff
	s_cbranch_scc1 .LBB0_140
	v_lshlrev_b32_e32 v2, 3, v1
	s_load_dwordx16 s[8:23], s[0:1], 0x0
	v_and_b32_e32 v8, 0x3f8, v2
	v_mov_b32_e32 v3, 0
	v_lshlrev_b32_e32 v2, 1, v8
	v_lshl_add_u64 v[4:5], s[66:67], 0, v[2:3]
	s_mov_b64 s[6:7], 0x1c00000
	v_lshlrev_b32_e32 v2, 2, v8
	v_lshl_add_u64 v[4:5], v[4:5], 0, s[6:7]
	v_lshl_add_u64 v[6:7], s[66:67], 0, v[2:3]
	s_mov_b64 s[6:7], 0x1a00000
	v_lshrrev_b32_e32 v10, 7, v1
	v_lshl_add_u64 v[6:7], v[6:7], 0, s[6:7]
	s_lshl_b32 s33, s2, 6
	s_lshl_b32 s40, s70, 6
	s_movk_i32 s41, 0xe000
	v_mov_b32_e32 v11, 0x6000
	s_mov_b64 s[38:39], 0x1000
	s_movk_i32 s42, 0x2000
	s_waitcnt lgkmcnt(0)
	v_mov_b32_e32 v12, s11
	v_mov_b32_e32 v13, s9
	v_mov_b32_e32 v14, s10
	v_mov_b32_e32 v15, s8
	v_lshlrev_b32_e32 v2, 2, v8
	s_movk_i32 s43, 0x1ffc
	s_movk_i32 s46, 0x1ff4
	s_movk_i32 s47, 0x1fec
	s_movk_i32 s48, 0x1fe4
	s_movk_i32 s49, 0x1000
	s_movk_i32 s56, 0x1fdc
	s_movk_i32 s57, 0x1fd4
	s_movk_i32 s58, 0x1fcc
	s_mov_b32 s59, s2
.LBB0_139:
	s_add_i32 s6, s33, s41
	v_add_u32_e32 v8, s33, v10
	s_lshr_b32 s6, s6, 12
	v_ashrrev_i32_e32 v9, 31, v8
	v_cmp_gt_i32_e32 vcc, s42, v8
	v_add_u32_e32 v17, 0xffffe000, v8
	v_add_u32_e32 v16, 4, v8
	v_add_u32_e32 v52, 0xffffe004, v8
	v_add_u32_e32 v18, 8, v8
	v_add_u32_e32 v20, 12, v8
	v_add_u32_e32 v22, 16, v8
	v_add_u32_e32 v24, 20, v8
	v_add_u32_e32 v26, 24, v8
	v_add_u32_e32 v28, 28, v8
	v_add_u32_e32 v30, 32, v8
	v_add_u32_e32 v32, 36, v8
	v_add_u32_e32 v34, 40, v8
	s_add_i32 s44, s6, 1
	v_cndmask_b32_e32 v47, 0, v9, vcc
	v_cndmask_b32_e32 v46, v17, v8, vcc
	v_cndmask_b32_e32 v49, v12, v13, vcc
	v_cndmask_b32_e32 v48, v14, v15, vcc
	v_ashrrev_i32_e32 v17, 31, v16
	v_cmp_gt_i32_e32 vcc, s43, v8
	v_add_u32_e32 v54, 0xffffe008, v8
	v_add_u32_e32 v58, 0xffffe00c, v8
	v_add_u32_e32 v62, 0xffffe010, v8
	v_add_u32_e32 v66, 0xffffe014, v8
	v_add_u32_e32 v70, 0xffffe018, v8
	v_add_u32_e32 v74, 0xffffe01c, v8
	v_add_u32_e32 v78, 0xffffe020, v8
	v_add_u32_e32 v80, 0xffffe024, v8
	v_add_u32_e32 v84, 0xffffe028, v8
	v_add_u32_e32 v36, 44, v8
	v_add_u32_e32 v88, 0xffffe02c, v8
	v_add_u32_e32 v38, 48, v8
	v_add_u32_e32 v92, 0xffffe030, v8
	v_add_u32_e32 v40, 52, v8
	v_add_u32_e32 v98, 0xffffe034, v8
	v_add_u32_e32 v42, 56, v8
	v_add_u32_e32 v102, 0xffffe038, v8
	v_add_u32_e32 v44, 60, v8
	v_add_u32_e32 v106, 0xffffe03c, v8
	v_ashrrev_i32_e32 v19, 31, v18
	v_cmp_gt_i32_e64 s[6:7], s42, v18
	v_ashrrev_i32_e32 v21, 31, v20
	v_cmp_gt_i32_e64 s[8:9], s46, v8
	v_ashrrev_i32_e32 v23, 31, v22
	v_cmp_gt_i32_e64 s[10:11], s42, v22
	v_ashrrev_i32_e32 v25, 31, v24
	v_cmp_gt_i32_e64 s[12:13], s47, v8
	v_ashrrev_i32_e32 v27, 31, v26
	v_cmp_gt_i32_e64 s[14:15], s42, v26
	v_ashrrev_i32_e32 v29, 31, v28
	v_cmp_gt_i32_e64 s[16:17], s48, v8
	v_lshlrev_b64 v[50:51], 11, v[8:9]
	v_ashrrev_i32_e32 v31, 31, v30
	v_cmp_gt_i32_e64 s[18:19], s42, v30
	v_ashrrev_i32_e32 v33, 31, v32
	v_cmp_gt_i32_e64 s[20:21], s56, v8
	v_ashrrev_i32_e32 v35, 31, v34
	v_cmp_gt_i32_e64 s[22:23], s42, v34
	v_cmp_gt_i32_e64 s[24:25], s57, v8
	v_cmp_gt_i32_e64 s[28:29], s58, v8
	s_cmpk_gt_i32 s59, 0x7f
	v_lshlrev_b64 v[8:9], 12, v[46:47]
	v_cndmask_b32_e32 v47, 0, v17, vcc
	v_cndmask_b32_e32 v46, v52, v16, vcc
	v_ashrrev_i32_e32 v37, 31, v36
	v_ashrrev_i32_e32 v39, 31, v38
	v_cmp_gt_i32_e64 s[26:27], s42, v38
	v_ashrrev_i32_e32 v41, 31, v40
	v_ashrrev_i32_e32 v43, 31, v42
	v_cmp_gt_i32_e64 s[30:31], s42, v42
	v_ashrrev_i32_e32 v45, 31, v44
	v_cmp_gt_i32_e64 s[34:35], s42, v44
	v_cndmask_b32_e32 v53, v12, v13, vcc
	v_cndmask_b32_e32 v52, v14, v15, vcc
	v_cndmask_b32_e64 v55, 0, v19, s[6:7]
	v_cndmask_b32_e64 v54, v54, v18, s[6:7]
	v_cndmask_b32_e64 v57, v12, v13, s[6:7]
	v_cndmask_b32_e64 v56, v14, v15, s[6:7]
	v_cndmask_b32_e64 v59, 0, v21, s[8:9]
	v_cndmask_b32_e64 v58, v58, v20, s[8:9]
	v_cndmask_b32_e64 v63, 0, v23, s[10:11]
	v_cndmask_b32_e64 v62, v62, v22, s[10:11]
	v_cndmask_b32_e64 v67, 0, v25, s[12:13]
	v_cndmask_b32_e64 v66, v66, v24, s[12:13]
	v_cndmask_b32_e64 v71, 0, v27, s[14:15]
	v_cndmask_b32_e64 v70, v70, v26, s[14:15]
	v_cndmask_b32_e64 v75, 0, v29, s[16:17]
	v_cndmask_b32_e64 v74, v74, v28, s[16:17]
	v_lshl_add_u64 v[96:97], v[4:5], 0, v[50:51]
	v_lshlrev_b64 v[16:17], 11, v[16:17]
	v_cndmask_b32_e64 v51, 0, v31, s[18:19]
	v_cndmask_b32_e64 v50, v78, v30, s[18:19]
	v_cndmask_b32_e64 v81, 0, v33, s[20:21]
	v_cndmask_b32_e64 v80, v80, v32, s[20:21]
	v_cndmask_b32_e64 v85, 0, v35, s[22:23]
	v_cndmask_b32_e64 v84, v84, v34, s[22:23]
	v_lshlrev_b64 v[30:31], 11, v[30:31]
	v_lshlrev_b64 v[110:111], 11, v[32:33]
	v_lshlrev_b64 v[112:113], 11, v[34:35]
	s_cselect_b32 s6, s44, 0
	v_lshl_add_u64 v[32:33], v[48:49], 0, v[8:9]
	v_lshlrev_b64 v[34:35], 12, v[46:47]
	v_cndmask_b32_e64 v61, v12, v13, s[8:9]
	v_cndmask_b32_e64 v60, v14, v15, s[8:9]
	v_cndmask_b32_e64 v65, v12, v13, s[10:11]
	v_cndmask_b32_e64 v64, v14, v15, s[10:11]
	v_cndmask_b32_e64 v69, v12, v13, s[12:13]
	v_cndmask_b32_e64 v68, v14, v15, s[12:13]
	v_cndmask_b32_e64 v73, v12, v13, s[14:15]
	v_cndmask_b32_e64 v72, v14, v15, s[14:15]
	v_cndmask_b32_e64 v77, v12, v13, s[16:17]
	v_cndmask_b32_e64 v76, v14, v15, s[16:17]
	v_lshlrev_b64 v[18:19], 11, v[18:19]
	v_lshlrev_b64 v[20:21], 11, v[20:21]
	v_lshlrev_b64 v[22:23], 11, v[22:23]
	v_lshlrev_b64 v[24:25], 11, v[24:25]
	v_lshlrev_b64 v[26:27], 11, v[26:27]
	v_lshlrev_b64 v[28:29], 11, v[28:29]
	v_cndmask_b32_e64 v89, 0, v37, s[24:25]
	v_cndmask_b32_e64 v88, v88, v36, s[24:25]
	v_cndmask_b32_e64 v93, 0, v39, s[26:27]
	v_cndmask_b32_e64 v92, v92, v38, s[26:27]
	v_cndmask_b32_e64 v99, 0, v41, s[28:29]
	v_cndmask_b32_e64 v98, v98, v40, s[28:29]
	v_cndmask_b32_e64 v103, 0, v43, s[30:31]
	v_cndmask_b32_e64 v102, v102, v42, s[30:31]
	v_cndmask_b32_e64 v107, 0, v45, s[34:35]
	v_cndmask_b32_e64 v106, v106, v44, s[34:35]
	v_lshlrev_b64 v[114:115], 11, v[36:37]
	v_lshlrev_b64 v[116:117], 11, v[38:39]
	v_lshlrev_b64 v[118:119], 11, v[40:41]
	v_lshlrev_b64 v[120:121], 11, v[42:43]
	v_lshlrev_b64 v[122:123], 11, v[44:45]
	v_lshlrev_b64 v[36:37], 12, v[54:55]
	v_lshlrev_b64 v[38:39], 12, v[58:59]
	v_lshlrev_b64 v[40:41], 12, v[62:63]
	v_lshlrev_b64 v[42:43], 12, v[66:67]
	v_lshlrev_b64 v[44:45], 12, v[70:71]
	v_lshlrev_b64 v[46:47], 12, v[74:75]
	v_lshl_add_u64 v[124:125], v[4:5], 0, v[16:17]
	v_lshlrev_b64 v[16:17], 12, v[50:51]
	v_lshl_add_u64 v[8:9], v[4:5], 0, v[30:31]
	v_mad_u64_u32 v[50:51], s[6:7], s6, v11, v[6:7]
	v_lshl_add_u64 v[30:31], v[32:33], 0, v[2:3]
	v_lshl_add_u64 v[32:33], v[52:53], 0, v[34:35]
	v_cndmask_b32_e64 v79, v12, v13, s[18:19]
	v_cndmask_b32_e64 v78, v14, v15, s[18:19]
	v_cndmask_b32_e64 v83, v12, v13, s[20:21]
	v_cndmask_b32_e64 v82, v14, v15, s[20:21]
	v_cndmask_b32_e64 v87, v12, v13, s[22:23]
	v_cndmask_b32_e64 v86, v14, v15, s[22:23]
	v_cndmask_b32_e64 v91, v12, v13, s[24:25]
	v_cndmask_b32_e64 v90, v14, v15, s[24:25]
	v_cndmask_b32_e64 v95, v12, v13, s[26:27]
	v_cndmask_b32_e64 v94, v14, v15, s[26:27]
	v_cndmask_b32_e64 v101, v12, v13, s[28:29]
	v_cndmask_b32_e64 v100, v14, v15, s[28:29]
	v_cndmask_b32_e64 v105, v12, v13, s[30:31]
	v_cndmask_b32_e64 v104, v14, v15, s[30:31]
	v_cndmask_b32_e64 v109, v12, v13, s[34:35]
	v_cndmask_b32_e64 v108, v14, v15, s[34:35]
	v_lshl_add_u64 v[126:127], v[4:5], 0, v[18:19]
	v_lshl_add_u64 v[128:129], v[4:5], 0, v[20:21]
	v_lshl_add_u64 v[130:131], v[4:5], 0, v[22:23]
	v_lshl_add_u64 v[132:133], v[4:5], 0, v[24:25]
	v_lshl_add_u64 v[134:135], v[4:5], 0, v[26:27]
	v_lshl_add_u64 v[136:137], v[4:5], 0, v[28:29]
	v_lshlrev_b64 v[18:19], 12, v[80:81]
	v_lshlrev_b64 v[20:21], 12, v[84:85]
	v_lshlrev_b64 v[22:23], 12, v[88:89]
	v_lshlrev_b64 v[24:25], 12, v[92:93]
	v_lshlrev_b64 v[26:27], 12, v[98:99]
	v_lshlrev_b64 v[28:29], 12, v[102:103]
	v_lshlrev_b64 v[48:49], 12, v[106:107]
	v_lshl_add_u64 v[34:35], v[56:57], 0, v[36:37]
	v_lshl_add_u64 v[36:37], v[60:61], 0, v[38:39]
	v_lshl_add_u64 v[38:39], v[64:65], 0, v[40:41]
	v_lshl_add_u64 v[40:41], v[68:69], 0, v[42:43]
	v_lshl_add_u64 v[42:43], v[72:73], 0, v[44:45]
	v_lshl_add_u64 v[44:45], v[76:77], 0, v[46:47]
	v_lshl_add_u64 v[66:67], v[32:33], 0, v[2:3]
	v_add_co_u32_e32 v32, vcc, s49, v50
	v_lshl_add_u64 v[46:47], v[78:79], 0, v[16:17]
	v_lshl_add_u64 v[52:53], v[82:83], 0, v[18:19]
	v_lshl_add_u64 v[54:55], v[86:87], 0, v[20:21]
	v_lshl_add_u64 v[56:57], v[90:91], 0, v[22:23]
	v_lshl_add_u64 v[58:59], v[94:95], 0, v[24:25]
	v_lshl_add_u64 v[60:61], v[100:101], 0, v[26:27]
	v_lshl_add_u64 v[62:63], v[104:105], 0, v[28:29]
	v_lshl_add_u64 v[48:49], v[108:109], 0, v[48:49]
	v_lshl_add_u64 v[64:65], v[50:51], 0, s[38:39]
	global_load_dwordx4 v[16:19], v[30:31], off offset:16
	global_load_dwordx4 v[20:23], v[30:31], off
	v_lshl_add_u64 v[68:69], v[34:35], 0, v[2:3]
	v_lshl_add_u64 v[70:71], v[36:37], 0, v[2:3]
	v_lshl_add_u64 v[72:73], v[38:39], 0, v[2:3]
	v_lshl_add_u64 v[76:77], v[40:41], 0, v[2:3]
	v_lshl_add_u64 v[84:85], v[42:43], 0, v[2:3]
	v_lshl_add_u64 v[92:93], v[44:45], 0, v[2:3]
	global_load_dwordx4 v[24:27], v[50:51], off offset:16
	global_load_dwordx4 v[28:31], v[50:51], off
	v_addc_co_u32_e32 v33, vcc, 0, v51, vcc
	v_lshl_add_u64 v[98:99], v[46:47], 0, v[2:3]
	v_lshl_add_u64 v[100:101], v[52:53], 0, v[2:3]
	v_lshl_add_u64 v[102:103], v[54:55], 0, v[2:3]
	v_lshl_add_u64 v[104:105], v[56:57], 0, v[2:3]
	v_lshl_add_u64 v[106:107], v[58:59], 0, v[2:3]
	v_lshl_add_u64 v[108:109], v[60:61], 0, v[2:3]
	v_lshl_add_u64 v[138:139], v[62:63], 0, v[2:3]
	v_lshl_add_u64 v[140:141], v[48:49], 0, v[2:3]
	global_load_dwordx4 v[32:35], v[32:33], off
	s_nop 0
	global_load_dwordx4 v[36:39], v[64:65], off offset:16
	global_load_dwordx4 v[40:43], v[66:67], off
	global_load_dwordx4 v[44:47], v[66:67], off offset:16
	global_load_dwordx4 v[48:51], v[68:69], off
	global_load_dwordx4 v[52:55], v[68:69], off offset:16
	global_load_dwordx4 v[56:59], v[70:71], off
	global_load_dwordx4 v[60:63], v[70:71], off offset:16
	s_nop 0
	global_load_dwordx4 v[64:67], v[72:73], off
	global_load_dwordx4 v[68:71], v[72:73], off offset:16
	s_nop 0
	global_load_dwordx4 v[72:75], v[76:77], off
	s_nop 0
	global_load_dwordx4 v[76:79], v[76:77], off offset:16
	s_nop 0
	global_load_dwordx4 v[80:83], v[84:85], off
	s_nop 0
	global_load_dwordx4 v[84:87], v[84:85], off offset:16
	s_nop 0
	global_load_dwordx4 v[88:91], v[92:93], off
	s_nop 0
	global_load_dwordx4 v[92:95], v[92:93], off offset:16
	s_add_i32 s59, s59, s70
	s_add_i32 s41, s41, s40
	v_add_u32_e32 v10, s40, v10
	s_cmpk_lt_i32 s59, 0x100
	s_waitcnt vmcnt(15)
	v_pk_add_f32 v[142:143], v[32:33], 1.0 op_sel_hi:[1,0]
	v_pk_add_f32 v[144:145], v[34:35], 1.0 op_sel_hi:[1,0]
	s_waitcnt vmcnt(14)
	v_pk_add_f32 v[146:147], v[36:37], 1.0 op_sel_hi:[1,0]
	v_pk_add_f32 v[148:149], v[38:39], 1.0 op_sel_hi:[1,0]
	v_pk_fma_f32 v[20:21], v[142:143], v[20:21], v[28:29]
	v_pk_fma_f32 v[22:23], v[144:145], v[22:23], v[30:31]
	v_pk_fma_f32 v[32:33], v[146:147], v[16:17], v[24:25]
	v_pk_fma_f32 v[34:35], v[148:149], v[18:19], v[26:27]
	s_waitcnt vmcnt(13)
	v_pk_fma_f32 v[36:37], v[142:143], v[40:41], v[28:29]
	v_pk_fma_f32 v[38:39], v[144:145], v[42:43], v[30:31]
	s_waitcnt vmcnt(12)
	v_pk_fma_f32 v[40:41], v[146:147], v[44:45], v[24:25]
	v_pk_fma_f32 v[42:43], v[148:149], v[46:47], v[26:27]
	s_waitcnt vmcnt(11)
	v_pk_fma_f32 v[44:45], v[142:143], v[48:49], v[28:29]
	v_pk_fma_f32 v[46:47], v[144:145], v[50:51], v[30:31]
	s_waitcnt vmcnt(10)
	v_pk_fma_f32 v[48:49], v[146:147], v[52:53], v[24:25]
	v_pk_fma_f32 v[50:51], v[148:149], v[54:55], v[26:27]
	s_waitcnt vmcnt(9)
	v_pk_fma_f32 v[52:53], v[142:143], v[56:57], v[28:29]
	v_pk_fma_f32 v[54:55], v[144:145], v[58:59], v[30:31]
	s_waitcnt vmcnt(8)
	v_pk_fma_f32 v[56:57], v[146:147], v[60:61], v[24:25]
	v_pk_fma_f32 v[58:59], v[148:149], v[62:63], v[26:27]
	s_waitcnt vmcnt(7)
	v_pk_fma_f32 v[60:61], v[142:143], v[64:65], v[28:29]
	v_pk_fma_f32 v[62:63], v[144:145], v[66:67], v[30:31]
	s_waitcnt vmcnt(6)
	v_pk_fma_f32 v[64:65], v[146:147], v[68:69], v[24:25]
	v_pk_fma_f32 v[66:67], v[148:149], v[70:71], v[26:27]
	s_waitcnt vmcnt(5)
	v_pk_fma_f32 v[68:69], v[142:143], v[72:73], v[28:29]
	v_pk_fma_f32 v[70:71], v[144:145], v[74:75], v[30:31]
	s_waitcnt vmcnt(4)
	v_pk_fma_f32 v[72:73], v[146:147], v[76:77], v[24:25]
	v_pk_fma_f32 v[74:75], v[148:149], v[78:79], v[26:27]
	s_waitcnt vmcnt(3)
	v_pk_fma_f32 v[76:77], v[142:143], v[80:81], v[28:29]
	v_pk_fma_f32 v[78:79], v[144:145], v[82:83], v[30:31]
	s_waitcnt vmcnt(2)
	v_pk_fma_f32 v[80:81], v[146:147], v[84:85], v[24:25]
	v_pk_fma_f32 v[82:83], v[148:149], v[86:87], v[26:27]
	s_waitcnt vmcnt(1)
	v_pk_fma_f32 v[84:85], v[142:143], v[88:89], v[28:29]
	v_pk_fma_f32 v[86:87], v[144:145], v[90:91], v[30:31]
	s_waitcnt vmcnt(0)
	v_pk_fma_f32 v[88:89], v[146:147], v[92:93], v[24:25]
	v_pk_fma_f32 v[90:91], v[148:149], v[94:95], v[26:27]
	v_cvt_pk_bf16_f32 v16, v20, v21
	v_cvt_pk_bf16_f32 v17, v22, v23
	v_cvt_pk_bf16_f32 v18, v32, v33
	v_cvt_pk_bf16_f32 v19, v34, v35
	v_cvt_pk_bf16_f32 v20, v36, v37
	v_cvt_pk_bf16_f32 v21, v38, v39
	v_cvt_pk_bf16_f32 v22, v40, v41
	v_cvt_pk_bf16_f32 v23, v42, v43
	v_cvt_pk_bf16_f32 v32, v44, v45
	v_cvt_pk_bf16_f32 v33, v46, v47
	v_cvt_pk_bf16_f32 v34, v48, v49
	v_cvt_pk_bf16_f32 v35, v50, v51
	v_cvt_pk_bf16_f32 v36, v52, v53
	v_cvt_pk_bf16_f32 v37, v54, v55
	v_cvt_pk_bf16_f32 v38, v56, v57
	v_cvt_pk_bf16_f32 v39, v58, v59
	v_cvt_pk_bf16_f32 v40, v60, v61
	v_cvt_pk_bf16_f32 v41, v62, v63
	v_cvt_pk_bf16_f32 v42, v64, v65
	v_cvt_pk_bf16_f32 v43, v66, v67
	v_cvt_pk_bf16_f32 v44, v68, v69
	v_cvt_pk_bf16_f32 v45, v70, v71
	v_cvt_pk_bf16_f32 v46, v72, v73
	v_cvt_pk_bf16_f32 v47, v74, v75
	v_cvt_pk_bf16_f32 v48, v76, v77
	v_cvt_pk_bf16_f32 v49, v78, v79
	v_cvt_pk_bf16_f32 v50, v80, v81
	v_cvt_pk_bf16_f32 v51, v82, v83
	v_cvt_pk_bf16_f32 v52, v84, v85
	v_cvt_pk_bf16_f32 v53, v86, v87
	v_cvt_pk_bf16_f32 v54, v88, v89
	v_cvt_pk_bf16_f32 v55, v90, v91
	global_store_dwordx4 v[96:97], v[16:19], off
	global_store_dwordx4 v[124:125], v[20:23], off
	global_store_dwordx4 v[126:127], v[32:35], off
	global_store_dwordx4 v[128:129], v[36:39], off
	global_store_dwordx4 v[130:131], v[40:43], off
	global_store_dwordx4 v[132:133], v[44:47], off
	global_store_dwordx4 v[134:135], v[48:51], off
	global_store_dwordx4 v[136:137], v[52:55], off
	global_load_dwordx4 v[16:19], v[98:99], off
	global_load_dwordx4 v[20:23], v[98:99], off offset:16
	global_load_dwordx4 v[32:35], v[100:101], off
	global_load_dwordx4 v[36:39], v[100:101], off offset:16
	global_load_dwordx4 v[40:43], v[102:103], off
	global_load_dwordx4 v[44:47], v[102:103], off offset:16
	global_load_dwordx4 v[48:51], v[104:105], off
	global_load_dwordx4 v[52:55], v[104:105], off offset:16
	global_load_dwordx4 v[56:59], v[106:107], off
	global_load_dwordx4 v[60:63], v[106:107], off offset:16
	global_load_dwordx4 v[64:67], v[108:109], off
	global_load_dwordx4 v[68:71], v[108:109], off offset:16
	global_load_dwordx4 v[72:75], v[138:139], off
	global_load_dwordx4 v[76:79], v[138:139], off offset:16
	global_load_dwordx4 v[80:83], v[140:141], off
	global_load_dwordx4 v[84:87], v[140:141], off offset:16
	v_lshl_add_u64 v[88:89], v[4:5], 0, v[110:111]
	v_lshl_add_u64 v[90:91], v[4:5], 0, v[112:113]
	v_lshl_add_u64 v[92:93], v[4:5], 0, v[114:115]
	v_lshl_add_u64 v[94:95], v[4:5], 0, v[116:117]
	v_lshl_add_u64 v[96:97], v[4:5], 0, v[118:119]
	v_lshl_add_u64 v[98:99], v[4:5], 0, v[120:121]
	v_lshl_add_u64 v[100:101], v[4:5], 0, v[122:123]
	s_waitcnt vmcnt(15)
	v_pk_fma_f32 v[16:17], v[142:143], v[16:17], v[28:29]
	v_pk_fma_f32 v[18:19], v[144:145], v[18:19], v[30:31]
	s_waitcnt vmcnt(14)
	v_pk_fma_f32 v[20:21], v[146:147], v[20:21], v[24:25]
	v_pk_fma_f32 v[22:23], v[148:149], v[22:23], v[26:27]
	s_waitcnt vmcnt(13)
	v_pk_fma_f32 v[32:33], v[142:143], v[32:33], v[28:29]
	v_pk_fma_f32 v[34:35], v[144:145], v[34:35], v[30:31]
	s_waitcnt vmcnt(12)
	v_pk_fma_f32 v[36:37], v[146:147], v[36:37], v[24:25]
	v_pk_fma_f32 v[38:39], v[148:149], v[38:39], v[26:27]
	s_waitcnt vmcnt(11)
	v_pk_fma_f32 v[40:41], v[142:143], v[40:41], v[28:29]
	v_pk_fma_f32 v[42:43], v[144:145], v[42:43], v[30:31]
	s_waitcnt vmcnt(10)
	v_pk_fma_f32 v[44:45], v[146:147], v[44:45], v[24:25]
	v_pk_fma_f32 v[46:47], v[148:149], v[46:47], v[26:27]
	s_waitcnt vmcnt(9)
	v_pk_fma_f32 v[48:49], v[142:143], v[48:49], v[28:29]
	v_pk_fma_f32 v[50:51], v[144:145], v[50:51], v[30:31]
	s_waitcnt vmcnt(8)
	v_pk_fma_f32 v[52:53], v[146:147], v[52:53], v[24:25]
	v_pk_fma_f32 v[54:55], v[148:149], v[54:55], v[26:27]
	s_waitcnt vmcnt(7)
	v_pk_fma_f32 v[56:57], v[142:143], v[56:57], v[28:29]
	v_pk_fma_f32 v[58:59], v[144:145], v[58:59], v[30:31]
	s_waitcnt vmcnt(6)
	v_pk_fma_f32 v[60:61], v[146:147], v[60:61], v[24:25]
	v_pk_fma_f32 v[62:63], v[148:149], v[62:63], v[26:27]
	s_waitcnt vmcnt(5)
	v_pk_fma_f32 v[64:65], v[142:143], v[64:65], v[28:29]
	v_pk_fma_f32 v[66:67], v[144:145], v[66:67], v[30:31]
	s_waitcnt vmcnt(4)
	v_pk_fma_f32 v[68:69], v[146:147], v[68:69], v[24:25]
	v_pk_fma_f32 v[70:71], v[148:149], v[70:71], v[26:27]
	s_waitcnt vmcnt(3)
	v_pk_fma_f32 v[72:73], v[142:143], v[72:73], v[28:29]
	v_pk_fma_f32 v[74:75], v[144:145], v[74:75], v[30:31]
	s_waitcnt vmcnt(2)
	v_pk_fma_f32 v[76:77], v[146:147], v[76:77], v[24:25]
	v_pk_fma_f32 v[78:79], v[148:149], v[78:79], v[26:27]
	s_waitcnt vmcnt(1)
	v_pk_fma_f32 v[80:81], v[142:143], v[80:81], v[28:29]
	v_pk_fma_f32 v[82:83], v[144:145], v[82:83], v[30:31]
	s_waitcnt vmcnt(0)
	v_pk_fma_f32 v[84:85], v[146:147], v[84:85], v[24:25]
	v_pk_fma_f32 v[86:87], v[148:149], v[86:87], v[26:27]
	v_cvt_pk_bf16_f32 v16, v16, v17
	v_cvt_pk_bf16_f32 v17, v18, v19
	v_cvt_pk_bf16_f32 v18, v20, v21
	v_cvt_pk_bf16_f32 v19, v22, v23
	v_cvt_pk_bf16_f32 v20, v32, v33
	v_cvt_pk_bf16_f32 v21, v34, v35
	v_cvt_pk_bf16_f32 v22, v36, v37
	v_cvt_pk_bf16_f32 v23, v38, v39
	v_cvt_pk_bf16_f32 v24, v40, v41
	v_cvt_pk_bf16_f32 v25, v42, v43
	v_cvt_pk_bf16_f32 v26, v44, v45
	v_cvt_pk_bf16_f32 v27, v46, v47
	v_cvt_pk_bf16_f32 v28, v48, v49
	v_cvt_pk_bf16_f32 v29, v50, v51
	v_cvt_pk_bf16_f32 v30, v52, v53
	v_cvt_pk_bf16_f32 v31, v54, v55
	v_cvt_pk_bf16_f32 v32, v56, v57
	v_cvt_pk_bf16_f32 v33, v58, v59
	v_cvt_pk_bf16_f32 v34, v60, v61
	v_cvt_pk_bf16_f32 v35, v62, v63
	v_cvt_pk_bf16_f32 v36, v64, v65
	v_cvt_pk_bf16_f32 v37, v66, v67
	v_cvt_pk_bf16_f32 v38, v68, v69
	v_cvt_pk_bf16_f32 v39, v70, v71
	v_cvt_pk_bf16_f32 v40, v72, v73
	v_cvt_pk_bf16_f32 v41, v74, v75
	v_cvt_pk_bf16_f32 v42, v76, v77
	v_cvt_pk_bf16_f32 v43, v78, v79
	v_cvt_pk_bf16_f32 v44, v80, v81
	v_cvt_pk_bf16_f32 v45, v82, v83
	v_cvt_pk_bf16_f32 v46, v84, v85
	v_cvt_pk_bf16_f32 v47, v86, v87
	global_store_dwordx4 v[8:9], v[16:19], off
	global_store_dwordx4 v[88:89], v[20:23], off
	global_store_dwordx4 v[90:91], v[24:27], off
	global_store_dwordx4 v[92:93], v[28:31], off
	global_store_dwordx4 v[94:95], v[32:35], off
	global_store_dwordx4 v[96:97], v[36:39], off
	global_store_dwordx4 v[98:99], v[40:43], off
	global_store_dwordx4 v[100:101], v[44:47], off
	s_cbranch_scc1 .LBB0_139
	s_cmpk_lg_u32 s70, 0x100
	s_cbranch_scc1 .Lp1_done
	s_bitcmp1_b32 s2, 3
	s_cbranch_scc0 .Lpf_begin
.Lp1_done:
.LBB0_140:
	s_cmp_gt_i32 s69, 2
	s_cselect_b64 s[6:7], -1, 0
	s_and_b64 s[8:9], s[36:37], s[6:7]
	s_andn2_b64 vcc, exec, s[8:9]
	s_cbranch_vccnz .LBB0_208
	s_cmpk_lt_u32 s69, 0x3e9
	s_mov_b64 s[8:9], -1
	s_cbranch_scc0 .LBB0_195
	s_waitcnt vmcnt(0)
	s_barrier
	s_mov_b64 s[8:9], exec
	v_readlane_b32 s10, v240, 4
	v_readlane_b32 s11, v240, 5
	s_and_b64 s[10:11], s[8:9], s[10:11]
	s_mov_b64 exec, s[10:11]
	s_cbranch_execz .LBB0_194
	s_add_i32 s10, 0, 0x26000
	v_mov_b32_e32 v2, s10
	s_waitcnt vmcnt(0) expcnt(0) lgkmcnt(0)
	ds_read_b32 v4, v2
	s_add_i32 s10, 0, 0x26004
	v_mov_b32_e32 v2, s10
	ds_read_b32 v2, v2
	s_waitcnt lgkmcnt(1)
	v_cmp_ne_u32_e32 vcc, 0, v4
	s_cbranch_vccnz .LBB0_158
	s_load_dword s10, s[0:1], 0x110
	s_mov_b32 s44, 1
	v_mov_b32_e32 v18, 0
	s_waitcnt lgkmcnt(0)
	s_mul_i32 s33, s71, s10
	s_add_u32 s10, s66, 0x1bc0200
	s_addc_u32 s11, s67, 0
	s_add_u32 s12, s66, 0x1bc0400
	s_addc_u32 s13, s67, 0
	s_add_u32 s14, s66, 0x1bc0500
	s_addc_u32 s15, s67, 0
	s_add_u32 s16, s66, 0x1bc0600
	s_addc_u32 s17, s67, 0
	s_add_u32 s18, s66, 0x1bc0700
	s_addc_u32 s19, s67, 0
	s_add_u32 s20, s66, 0x1bc0800
	s_addc_u32 s21, s67, 0
	s_add_u32 s22, s66, 0x1bc0900
	s_addc_u32 s23, s67, 0
	s_add_u32 s24, s66, 0x1bc0a00
	s_addc_u32 s25, s67, 0
	s_add_u32 s26, s66, 0x1bc0b00
	s_addc_u32 s27, s67, 0
	s_add_u32 s28, s66, 0x1bc0c00
	s_addc_u32 s29, s67, 0
	s_add_u32 s30, s66, 0x1bc0d00
	s_addc_u32 s31, s67, 0
	s_add_u32 s34, s66, 0x1bc0e00
	s_addc_u32 s35, s67, 0
	s_add_u32 s36, s66, 0x1bc0f00
	s_addc_u32 s37, s67, 0
	s_add_u32 s38, s66, 0x1bc1000
	s_addc_u32 s39, s67, 0
	s_add_u32 s40, s66, 0x1bc1100
	s_addc_u32 s41, s67, 0
	s_add_u32 s42, s66, 0x1bc1200
	s_addc_u32 s43, s67, 0
	s_add_u32 s48, s66, 0x1bc1300
	s_mul_i32 s33, s33, s70
	s_addc_u32 s49, s67, 0
	s_branch .LBB0_146

.LBB0_224:
	s_waitcnt vmcnt(0)
	v_readlane_b32 s0, v240, 22
	v_readlane_b32 s1, v240, 23
	s_barrier
	s_cmpk_lg_u32 s70, 0x100
	s_cbranch_scc1 .Lpf_begin
	s_branch .Lpf_done

.Lpf_end:
	s_cmpk_lg_u32 s70, 0x100
	s_cbranch_scc1 .Lpf_done
	s_bitcmp1_b32 s2, 3
	s_cbranch_scc1 .Lp1_body
	s_branch .Lp1_done
